# F1 LoRA MFMA tiles: the two late weight-fragment LDS reads of tiles 1 and 2 issued with the first four (counted lgkmcnt) instead of read-wait-MFMA
# baseline (speedup 1.0000x reference)
.LBB0_588:
	ds_read_b128 v[36:39], v216 offset:2304
	ds_read_b128 v[60:63], v216 offset:2368
	ds_read_b128 v[48:51], v216 offset:11520
	ds_read_b128 v[52:55], v216 offset:29952
	ds_read_b128 v[226:229], v216 offset:11584
	ds_read_b128 v[230:233], v216 offset:30016
	s_and_b64 vcc, exec, s[0:1]
	s_waitcnt lgkmcnt(5)
	v_mfma_f32_16x16x32_bf16 v[36:39], v[36:39], v[72:75], 0
	s_waitcnt lgkmcnt(4)
	v_mfma_f32_16x16x32_bf16 v[100:103], v[60:63], v[132:135], v[36:39]
	s_waitcnt lgkmcnt(3)
	v_mfma_f32_16x16x32_bf16 v[48:51], v[48:51], v[108:111], 0
	s_waitcnt lgkmcnt(1)
	v_mfma_f32_16x16x32_bf16 v[96:99], v[226:229], v[136:139], v[48:51]
	v_mfma_f32_16x16x32_bf16 v[52:55], v[52:55], v[128:131], 0
	s_waitcnt lgkmcnt(0)
	v_mfma_f32_16x16x32_bf16 v[92:95], v[230:233], v[56:59], v[52:55]
	s_cbranch_vccnz .LBB0_590
	ds_read_b128 v[36:39], v216 offset:20736
	s_waitcnt lgkmcnt(0)
	v_mfma_f32_16x16x32_bf16 v[104:107], v[36:39], v[140:143], 0
	s_branch .LBB0_591

.LBB0_591:
	ds_read_b128 v[36:39], v216 offset:4608
	ds_read_b128 v[60:63], v216 offset:4672
	ds_read_b128 v[48:51], v216 offset:13824
	ds_read_b128 v[52:55], v216 offset:32256
	ds_read_b128 v[226:229], v216 offset:13888
	ds_read_b128 v[230:233], v216 offset:32320
	s_and_b64 vcc, exec, s[0:1]
	s_waitcnt lgkmcnt(5)
	v_mfma_f32_16x16x32_bf16 v[36:39], v[36:39], v[72:75], 0
	s_waitcnt lgkmcnt(4)
	v_mfma_f32_16x16x32_bf16 v[80:83], v[60:63], v[132:135], v[36:39]
	s_waitcnt lgkmcnt(3)
	v_mfma_f32_16x16x32_bf16 v[48:51], v[48:51], v[108:111], 0
	s_waitcnt lgkmcnt(1)
	v_mfma_f32_16x16x32_bf16 v[68:71], v[226:229], v[136:139], v[48:51]
	v_mfma_f32_16x16x32_bf16 v[52:55], v[52:55], v[128:131], 0
	s_waitcnt lgkmcnt(0)
	v_mfma_f32_16x16x32_bf16 v[60:63], v[230:233], v[56:59], v[52:55]
	s_cbranch_vccnz .LBB0_593
	ds_read_b128 v[36:39], v216 offset:23040
	s_waitcnt lgkmcnt(0)
	v_mfma_f32_16x16x32_bf16 v[84:87], v[36:39], v[140:143], 0
	s_branch .LBB0_594
